# adds GLU in-place rescale loop load hoisting (with store-data WAR pad), reduce_tail split-4 fast path issuing the four partial loads together, attention item-top vmcnt(0) drain removed
# baseline (speedup 1.0000x reference)
; __device__ __forceinline__ unsigned pk2(float lo, float hi) { const f32x2 v = {lo, hi}; return __builtin_bit_cast(unsigned, __builtin_convertvector(v, bf16x2_t)); }
; __device__ __forceinline__ void unpack8(u32x4 w, float* f) { f[0] = bflo(w.x); f[1] = bfhi(w.x); f[2] = bflo(w.y); f[3] = bfhi(w.y); f[4] = bflo(w.z); f[5] = bfhi(w.z); f[6] = bflo(w.w); f[7] = bfhi(w.w); }
; __global__ void __launch_bounds__(512, 2) mega(Args a_) {
;     ...
;                             for (int bj = 0; bj < 2; ++bj) { const int col = pn * 256 + wc * 32 + 8 * fq + bj * 128;
;                                 const f32x4 g0 = *(const f32x4*)(a->in[26] + l * D + col), g1 = *(const f32x4*)(a->in[26] + l * D + col + 4);
; #pragma unroll
;                                 for (int am = 0; am < 8; ++am) { const int rl = wr * 64 + fr + (am >> 2) * 128 + (am & 3) * 16; bf16_t* yp = XN + ((size_t)bx * 256 + rl) * D + col;
;                                     const float rs = rsqrtf(rss[rl] * (1.0f / 512.0f) + EPS); float y[8]; unpack8(*(const u32x4*)yp, y);
;                                     u32x4 w; w.x = pk2(y[0] * rs * g0[0], y[1] * rs * g0[1]); w.y = pk2(y[2] * rs * g0[2], y[3] * rs * g0[3]); w.z = pk2(y[4] * rs * g1[0], y[5] * rs * g1[1]); w.w = pk2(y[6] * rs * g1[2], y[7] * rs * g1[3]);
;                                     *(u32x4*)yp = w; } } }
.LBB0_111:
	v_or_b32_e32 v160, s2, v33
	v_lshl_add_u64 v[46:47], v[160:161], 1, s[6:7]
	v_cndmask_b32_e64 v34, 0, 1, s[10:11]
	v_lshl_add_u64 v[38:39], v[160:161], 2, s[4:5]
	v_lshl_add_u64 v[48:49], v[46:47], 0, v[0:1]
	v_cmp_ne_u32_e32 vcc, 1, v34
	global_load_dwordx4 v[34:37], v[38:39], off offset:16
	s_nop 0
	global_load_dwordx4 v[38:41], v[38:39], off
	s_movk_i32 s2, 0x80
	v_lshl_add_u64 v[96:97], v[46:47], 0, v[0:1]
	global_load_dwordx4 v[64:67], v[96:97], off
	v_lshl_add_u64 v[96:97], v[46:47], 0, v[4:5]
	global_load_dwordx4 v[68:71], v[96:97], off
	v_lshl_add_u64 v[96:97], v[46:47], 0, v[8:9]
	global_load_dwordx4 v[72:75], v[96:97], off
	v_lshl_add_u64 v[96:97], v[46:47], 0, v[12:13]
	global_load_dwordx4 v[76:79], v[96:97], off
	v_lshl_add_u64 v[96:97], v[46:47], 0, v[16:17]
	global_load_dwordx4 v[80:83], v[96:97], off
	v_lshl_add_u64 v[96:97], v[46:47], 0, v[20:21]
	global_load_dwordx4 v[84:87], v[96:97], off
	v_lshl_add_u64 v[96:97], v[46:47], 0, v[24:25]
	global_load_dwordx4 v[88:91], v[96:97], off
	v_lshl_add_u64 v[96:97], v[46:47], 0, v[28:29]
	global_load_dwordx4 v[92:95], v[96:97], off
	s_mov_b64 s[10:11], 0
	s_and_b64 vcc, exec, vcc
	s_waitcnt vmcnt(7)
	s_nop 1
	v_mov_b32_e32 v42, v64
	v_mov_b32_e32 v43, v65
	v_mov_b32_e32 v44, v66
	v_mov_b32_e32 v45, v67
	v_lshlrev_b32_e32 v50, 16, v42
	v_and_b32_e32 v51, 0xffff0000, v42
	v_pk_mul_f32 v[50:51], v[2:3], v[50:51]
	s_nop 0
	v_pk_mul_f32 v[50:51], v[38:39], v[50:51]
	s_nop 0
	v_cvt_pk_bf16_f32 v42, v50, v51
	v_lshlrev_b32_e32 v50, 16, v43
	v_and_b32_e32 v51, 0xffff0000, v43
	v_pk_mul_f32 v[50:51], v[2:3], v[50:51]
	s_nop 0
	v_pk_mul_f32 v[50:51], v[40:41], v[50:51]
	s_nop 0
	v_cvt_pk_bf16_f32 v43, v50, v51
	v_lshlrev_b32_e32 v50, 16, v44
	v_and_b32_e32 v51, 0xffff0000, v44
	v_pk_mul_f32 v[50:51], v[2:3], v[50:51]
	s_nop 0
	v_pk_mul_f32 v[50:51], v[34:35], v[50:51]
	s_nop 0
	v_cvt_pk_bf16_f32 v44, v50, v51
	v_lshlrev_b32_e32 v50, 16, v45
	v_and_b32_e32 v51, 0xffff0000, v45
	v_pk_mul_f32 v[50:51], v[2:3], v[50:51]
	s_nop 0
	v_pk_mul_f32 v[50:51], v[36:37], v[50:51]
	s_nop 0
	v_cvt_pk_bf16_f32 v45, v50, v51
	global_store_dwordx4 v[48:49], v[42:45], off
	v_lshl_add_u64 v[48:49], v[46:47], 0, v[4:5]
	s_waitcnt vmcnt(7)
	s_nop 1
	v_mov_b32_e32 v42, v68
	v_mov_b32_e32 v43, v69
	v_mov_b32_e32 v44, v70
	v_mov_b32_e32 v45, v71
	v_lshlrev_b32_e32 v50, 16, v42
	v_and_b32_e32 v51, 0xffff0000, v42
	v_pk_mul_f32 v[50:51], v[6:7], v[50:51]
	s_nop 0
	v_pk_mul_f32 v[50:51], v[38:39], v[50:51]
	s_nop 0
	v_cvt_pk_bf16_f32 v42, v50, v51
	v_lshlrev_b32_e32 v50, 16, v43
	v_and_b32_e32 v51, 0xffff0000, v43
	v_pk_mul_f32 v[50:51], v[6:7], v[50:51]
	s_nop 0
	v_pk_mul_f32 v[50:51], v[40:41], v[50:51]
	s_nop 0
	v_cvt_pk_bf16_f32 v43, v50, v51
	v_lshlrev_b32_e32 v50, 16, v44
	v_and_b32_e32 v51, 0xffff0000, v44
	v_pk_mul_f32 v[50:51], v[6:7], v[50:51]
	s_nop 0
	v_pk_mul_f32 v[50:51], v[34:35], v[50:51]
	s_nop 0
	v_cvt_pk_bf16_f32 v44, v50, v51
	v_lshlrev_b32_e32 v50, 16, v45
	v_and_b32_e32 v51, 0xffff0000, v45
	v_pk_mul_f32 v[50:51], v[6:7], v[50:51]
	s_nop 0
	v_pk_mul_f32 v[50:51], v[36:37], v[50:51]
	s_nop 0
	v_cvt_pk_bf16_f32 v45, v50, v51
	global_store_dwordx4 v[48:49], v[42:45], off
	v_lshl_add_u64 v[48:49], v[46:47], 0, v[8:9]
	s_waitcnt vmcnt(7)
	s_nop 1
	v_mov_b32_e32 v42, v72
	v_mov_b32_e32 v43, v73
	v_mov_b32_e32 v44, v74
	v_mov_b32_e32 v45, v75
	v_lshlrev_b32_e32 v50, 16, v42
	v_and_b32_e32 v51, 0xffff0000, v42
	v_pk_mul_f32 v[50:51], v[10:11], v[50:51]
	s_nop 0
	v_pk_mul_f32 v[50:51], v[38:39], v[50:51]
	s_nop 0
	v_cvt_pk_bf16_f32 v42, v50, v51
	v_lshlrev_b32_e32 v50, 16, v43
	v_and_b32_e32 v51, 0xffff0000, v43
	v_pk_mul_f32 v[50:51], v[10:11], v[50:51]
	s_nop 0
	v_pk_mul_f32 v[50:51], v[40:41], v[50:51]
	s_nop 0
	v_cvt_pk_bf16_f32 v43, v50, v51
	v_lshlrev_b32_e32 v50, 16, v44
	v_and_b32_e32 v51, 0xffff0000, v44
	v_pk_mul_f32 v[50:51], v[10:11], v[50:51]
	s_nop 0
	v_pk_mul_f32 v[50:51], v[34:35], v[50:51]
	s_nop 0
	v_cvt_pk_bf16_f32 v44, v50, v51
	v_lshlrev_b32_e32 v50, 16, v45
	v_and_b32_e32 v51, 0xffff0000, v45
	v_pk_mul_f32 v[50:51], v[10:11], v[50:51]
	s_nop 0
	v_pk_mul_f32 v[50:51], v[36:37], v[50:51]
	s_nop 0
	v_cvt_pk_bf16_f32 v45, v50, v51
	global_store_dwordx4 v[48:49], v[42:45], off
	v_lshl_add_u64 v[48:49], v[46:47], 0, v[12:13]
	s_waitcnt vmcnt(7)
; __device__ __forceinline__ unsigned pk2(float lo, float hi) { const f32x2 v = {lo, hi}; return __builtin_bit_cast(unsigned, __builtin_convertvector(v, bf16x2_t)); }
; __device__ __forceinline__ void unpack8(u32x4 w, float* f) { f[0] = bflo(w.x); f[1] = bfhi(w.x); f[2] = bflo(w.y); f[3] = bfhi(w.y); f[4] = bflo(w.z); f[5] = bfhi(w.z); f[6] = bflo(w.w); f[7] = bfhi(w.w); }
; __global__ void __launch_bounds__(512, 2) mega(Args a_) {
;     ...
;                             for (int bj = 0; bj < 2; ++bj) { const int col = pn * 256 + wc * 32 + 8 * fq + bj * 128;
;                                 const f32x4 g0 = *(const f32x4*)(a->in[26] + l * D + col), g1 = *(const f32x4*)(a->in[26] + l * D + col + 4);
; #pragma unroll
;                                 for (int am = 0; am < 8; ++am) { const int rl = wr * 64 + fr + (am >> 2) * 128 + (am & 3) * 16; bf16_t* yp = XN + ((size_t)bx * 256 + rl) * D + col;
;                                     const float rs = rsqrtf(rss[rl] * (1.0f / 512.0f) + EPS); float y[8]; unpack8(*(const u32x4*)yp, y);
;                                     u32x4 w; w.x = pk2(y[0] * rs * g0[0], y[1] * rs * g0[1]); w.y = pk2(y[2] * rs * g0[2], y[3] * rs * g0[3]); w.z = pk2(y[4] * rs * g1[0], y[5] * rs * g1[1]); w.w = pk2(y[6] * rs * g1[2], y[7] * rs * g1[3]);
;                                     *(u32x4*)yp = w; } } }
	s_nop 1
	v_mov_b32_e32 v42, v76
	v_mov_b32_e32 v43, v77
	v_mov_b32_e32 v44, v78
	v_mov_b32_e32 v45, v79
	v_lshlrev_b32_e32 v50, 16, v42
	v_and_b32_e32 v51, 0xffff0000, v42
	v_pk_mul_f32 v[50:51], v[14:15], v[50:51]
	s_nop 0
	v_pk_mul_f32 v[50:51], v[38:39], v[50:51]
	s_nop 0
	v_cvt_pk_bf16_f32 v42, v50, v51
	v_lshlrev_b32_e32 v50, 16, v43
	v_and_b32_e32 v51, 0xffff0000, v43
	v_pk_mul_f32 v[50:51], v[14:15], v[50:51]
	s_nop 0
	v_pk_mul_f32 v[50:51], v[40:41], v[50:51]
	s_nop 0
	v_cvt_pk_bf16_f32 v43, v50, v51
	v_lshlrev_b32_e32 v50, 16, v44
	v_and_b32_e32 v51, 0xffff0000, v44
	v_pk_mul_f32 v[50:51], v[14:15], v[50:51]
	s_nop 0
	v_pk_mul_f32 v[50:51], v[34:35], v[50:51]
	s_nop 0
	v_cvt_pk_bf16_f32 v44, v50, v51
	v_lshlrev_b32_e32 v50, 16, v45
	v_and_b32_e32 v51, 0xffff0000, v45
	v_pk_mul_f32 v[50:51], v[14:15], v[50:51]
	s_nop 0
	v_pk_mul_f32 v[50:51], v[36:37], v[50:51]
	s_nop 0
	v_cvt_pk_bf16_f32 v45, v50, v51
	global_store_dwordx4 v[48:49], v[42:45], off
	v_lshl_add_u64 v[48:49], v[46:47], 0, v[16:17]
	s_waitcnt vmcnt(7)
	s_nop 1
	v_mov_b32_e32 v42, v80
	v_mov_b32_e32 v43, v81
	v_mov_b32_e32 v44, v82
	v_mov_b32_e32 v45, v83
	v_lshlrev_b32_e32 v50, 16, v42
	v_and_b32_e32 v51, 0xffff0000, v42
	v_pk_mul_f32 v[50:51], v[18:19], v[50:51]
	s_nop 0
	v_pk_mul_f32 v[50:51], v[38:39], v[50:51]
	s_nop 0
	v_cvt_pk_bf16_f32 v42, v50, v51
	v_lshlrev_b32_e32 v50, 16, v43
	v_and_b32_e32 v51, 0xffff0000, v43
	v_pk_mul_f32 v[50:51], v[18:19], v[50:51]
	s_nop 0
	v_pk_mul_f32 v[50:51], v[40:41], v[50:51]
	s_nop 0
	v_cvt_pk_bf16_f32 v43, v50, v51
	v_lshlrev_b32_e32 v50, 16, v44
	v_and_b32_e32 v51, 0xffff0000, v44
	v_pk_mul_f32 v[50:51], v[18:19], v[50:51]
	s_nop 0
	v_pk_mul_f32 v[50:51], v[34:35], v[50:51]
	s_nop 0
	v_cvt_pk_bf16_f32 v44, v50, v51
	v_lshlrev_b32_e32 v50, 16, v45
	v_and_b32_e32 v51, 0xffff0000, v45
	v_pk_mul_f32 v[50:51], v[18:19], v[50:51]
	s_nop 0
	v_pk_mul_f32 v[50:51], v[36:37], v[50:51]
	s_nop 0
	v_cvt_pk_bf16_f32 v45, v50, v51
	global_store_dwordx4 v[48:49], v[42:45], off
	v_lshl_add_u64 v[48:49], v[46:47], 0, v[20:21]
	s_waitcnt vmcnt(7)
	s_nop 1
	v_mov_b32_e32 v42, v84
	v_mov_b32_e32 v43, v85
	v_mov_b32_e32 v44, v86
	v_mov_b32_e32 v45, v87
	v_lshlrev_b32_e32 v50, 16, v42
	v_and_b32_e32 v51, 0xffff0000, v42
	v_pk_mul_f32 v[50:51], v[22:23], v[50:51]
	s_nop 0
	v_pk_mul_f32 v[50:51], v[38:39], v[50:51]
	s_nop 0
	v_cvt_pk_bf16_f32 v42, v50, v51
	v_lshlrev_b32_e32 v50, 16, v43
	v_and_b32_e32 v51, 0xffff0000, v43
	v_pk_mul_f32 v[50:51], v[22:23], v[50:51]
	s_nop 0
	v_pk_mul_f32 v[50:51], v[40:41], v[50:51]
	s_nop 0
	v_cvt_pk_bf16_f32 v43, v50, v51
	v_lshlrev_b32_e32 v50, 16, v44
	v_and_b32_e32 v51, 0xffff0000, v44
	v_pk_mul_f32 v[50:51], v[22:23], v[50:51]
	s_nop 0
	v_pk_mul_f32 v[50:51], v[34:35], v[50:51]
	s_nop 0
	v_cvt_pk_bf16_f32 v44, v50, v51
	v_lshlrev_b32_e32 v50, 16, v45
	v_and_b32_e32 v51, 0xffff0000, v45
	v_pk_mul_f32 v[50:51], v[22:23], v[50:51]
	s_nop 0
	v_pk_mul_f32 v[50:51], v[36:37], v[50:51]
	s_nop 0
	v_cvt_pk_bf16_f32 v45, v50, v51
	global_store_dwordx4 v[48:49], v[42:45], off
	v_lshl_add_u64 v[48:49], v[46:47], 0, v[24:25]
	v_lshl_add_u64 v[46:47], v[46:47], 0, v[28:29]
	s_waitcnt vmcnt(7)
	s_nop 1
	v_mov_b32_e32 v42, v88
	v_mov_b32_e32 v43, v89
	v_mov_b32_e32 v44, v90
	v_mov_b32_e32 v45, v91
	v_lshlrev_b32_e32 v50, 16, v42
	v_and_b32_e32 v51, 0xffff0000, v42
	v_pk_mul_f32 v[50:51], v[26:27], v[50:51]
	s_nop 0
	v_pk_mul_f32 v[50:51], v[38:39], v[50:51]
	s_nop 0
	v_cvt_pk_bf16_f32 v42, v50, v51
	v_lshlrev_b32_e32 v50, 16, v43
	v_and_b32_e32 v51, 0xffff0000, v43
	v_pk_mul_f32 v[50:51], v[26:27], v[50:51]
	s_nop 0
	v_pk_mul_f32 v[50:51], v[40:41], v[50:51]
	s_nop 0
	v_cvt_pk_bf16_f32 v43, v50, v51
	v_lshlrev_b32_e32 v50, 16, v44
	v_and_b32_e32 v51, 0xffff0000, v44
	v_pk_mul_f32 v[50:51], v[26:27], v[50:51]
	s_nop 0
	v_pk_mul_f32 v[50:51], v[34:35], v[50:51]
	s_nop 0
	v_cvt_pk_bf16_f32 v44, v50, v51
	v_lshlrev_b32_e32 v50, 16, v45
	v_and_b32_e32 v51, 0xffff0000, v45
	v_pk_mul_f32 v[50:51], v[26:27], v[50:51]
	s_nop 0
	v_pk_mul_f32 v[50:51], v[36:37], v[50:51]
	s_nop 0
	v_cvt_pk_bf16_f32 v45, v50, v51
	global_store_dwordx4 v[48:49], v[42:45], off
	s_waitcnt vmcnt(7)
	s_nop 1
	v_mov_b32_e32 v42, v92
	v_mov_b32_e32 v43, v93
	v_mov_b32_e32 v44, v94
	v_mov_b32_e32 v45, v95
	v_lshlrev_b32_e32 v48, 16, v42
	v_and_b32_e32 v49, 0xffff0000, v42
	v_lshlrev_b32_e32 v42, 16, v43
	v_and_b32_e32 v43, 0xffff0000, v43
	v_pk_mul_f32 v[48:49], v[30:31], v[48:49]
	v_pk_mul_f32 v[42:43], v[30:31], v[42:43]
	v_pk_mul_f32 v[38:39], v[38:39], v[48:49]
	v_pk_mul_f32 v[40:41], v[40:41], v[42:43]
	v_cvt_pk_bf16_f32 v38, v38, v39
	v_cvt_pk_bf16_f32 v39, v40, v41
	v_lshlrev_b32_e32 v40, 16, v44
	v_and_b32_e32 v41, 0xffff0000, v44
	v_pk_mul_f32 v[40:41], v[30:31], v[40:41]
	s_nop 0
	v_pk_mul_f32 v[34:35], v[34:35], v[40:41]
	s_nop 0
	v_cvt_pk_bf16_f32 v40, v34, v35
	v_lshlrev_b32_e32 v34, 16, v45
	v_and_b32_e32 v35, 0xffff0000, v45
	v_pk_mul_f32 v[34:35], v[30:31], v[34:35]
	s_nop 0
	v_pk_mul_f32 v[34:35], v[36:37], v[34:35]
	s_nop 0
	v_cvt_pk_bf16_f32 v41, v34, v35
	global_store_dwordx4 v[46:47], v[38:41], off
	s_cbranch_vccz .LBB0_111
	s_movk_i32 s10, 0x100
	s_mov_b64 s[2:3], 0
	s_and_b64 vcc, exec, s[8:9]
	s_cbranch_vccz .LBB0_110

; __device__ __forceinline__ void attn_phase(CArgs a, int l, LAS unsigned char* lds, int tid, int lane, int wave, int G, int bx) {
;     ...
;     for (int it = (bx + 64) % G; it < 1088; it += G) {
;         int ll = l; asm volatile("" : "+s"(ll));
;         const bool pr = it < 1024; const int half = it & 1;
;         const int bc = pr ? (it >> 1) : 0, c = bc & 255, b = bc >> 8, sb = pr ? 0 : ((it - 1024) >> 1);
;         const int token0 = (pr ? bc * 64 : TP + sb * 64) + half * 32;
;         __syncthreads();
.LBB0_277:
	s_cmpk_gt_i32 s20, 0x3ff
	s_cselect_b64 s[6:7], -1, 0
	s_ashr_i32 s2, s20, 1
	s_cmpk_lt_i32 s20, 0x400
	s_cselect_b64 s[8:9], -1, 0
	s_and_b64 s[0:1], s[8:9], exec
	v_readlane_b32 s88, v254, 24
	s_cselect_b32 s14, s2, 0
	s_and_b64 vcc, exec, s[6:7]
	s_nop 0
	s_barrier
	s_cbranch_vccz .LBB0_279
	v_readlane_b32 s0, v255, 32
	v_readlane_b32 s1, v255, 33
	s_mov_b64 s[2:3], 0
	s_and_b64 s[0:1], s[0:1], exec
	s_branch .LBB0_280

; template <class Order>
; __device__ __forceinline__ void reduce_tail(const Order& S, const float* PART, const float* gate, const XBuf xin, const XBuf xout, int lane, int wave, int G, int bx) {
;     ...
;     for (int it = bx; it < (S.nwg - S.nfull) * S.split; it += G) { int pm, pn; S.tile_of(S.nfull + it / S.split, pm, pn);
;         const int r0 = (it % S.split) * rows, c8 = (lane & 31) * 8;
;         for (int rl = r0 + wave * 2 + (lane >> 5); rl < r0 + rows; rl += 16) { const int row = pm * 256 + rl, col = pn * 256 + c8;
;             f32x4 s0 = {0.f, 0.f, 0.f, 0.f}, s1 = {0.f, 0.f, 0.f, 0.f};
;             for (int p = 0; p < S.split; ++p) { const float* pp = PART + ((size_t)((it / S.split) * S.split + p) * 256 + rl) * 256 + c8; s0 += *(const f32x4*)pp; s1 += *(const f32x4*)(pp + 4); }
.LBB0_746:
	v_ashrrev_i32_e32 v19, 31, v18
	v_lshlrev_b64 v[0:1], 10, v[18:19]
	v_mov_b32_e32 v32, 0
	v_lshl_add_u64 v[0:1], v[16:17], 0, v[0:1]
	s_mov_b32 s12, s22
	s_mov_b32 s2, s44
	v_mov_b32_e32 v33, v32
	v_mov_b32_e32 v28, v32
	v_mov_b32_e32 v29, v32
	v_mov_b32_e32 v30, v32
	v_mov_b32_e32 v31, v32
	v_mov_b32_e32 v26, v32
	v_mov_b32_e32 v27, v32
	s_cmp_eq_u32 s2, 4
	s_cbranch_scc0 .LBB0_747
	s_ashr_i32 s13, s12, 31
	s_lshl_b64 s[26:27], s[12:13], 18
	v_lshl_add_u64 v[6:7], v[0:1], 0, s[26:27]
	global_load_dwordx4 v[2:5], v[6:7], off
	global_load_dwordx4 v[40:43], v[6:7], off offset:16
	s_add_u32 s26, s26, 0x40000
	s_addc_u32 s27, s27, 0
	v_lshl_add_u64 v[6:7], v[0:1], 0, s[26:27]
	global_load_dwordx4 v[44:47], v[6:7], off
	global_load_dwordx4 v[48:51], v[6:7], off offset:16
	s_add_u32 s26, s26, 0x40000
	s_addc_u32 s27, s27, 0
	v_lshl_add_u64 v[6:7], v[0:1], 0, s[26:27]
	global_load_dwordx4 v[52:55], v[6:7], off
	global_load_dwordx4 v[56:59], v[6:7], off offset:16
	s_add_u32 s26, s26, 0x40000
	s_addc_u32 s27, s27, 0
	v_lshl_add_u64 v[6:7], v[0:1], 0, s[26:27]
	global_load_dwordx4 v[60:63], v[6:7], off
	global_load_dwordx4 v[64:67], v[6:7], off offset:16
	s_add_i32 s12, s12, 4
	s_mov_b32 s2, 0
	s_waitcnt vmcnt(0)
	v_pk_add_f32 v[28:29], v[28:29], v[4:5]
	v_pk_add_f32 v[32:33], v[32:33], v[2:3]
	v_pk_add_f32 v[26:27], v[26:27], v[42:43]
	v_pk_add_f32 v[30:31], v[30:31], v[40:41]
	v_pk_add_f32 v[28:29], v[28:29], v[46:47]
	v_pk_add_f32 v[32:33], v[32:33], v[44:45]
	v_pk_add_f32 v[26:27], v[26:27], v[50:51]
	v_pk_add_f32 v[30:31], v[30:31], v[48:49]
	v_pk_add_f32 v[28:29], v[28:29], v[54:55]
	v_pk_add_f32 v[32:33], v[32:33], v[52:53]
	v_pk_add_f32 v[26:27], v[26:27], v[58:59]
	v_pk_add_f32 v[30:31], v[30:31], v[56:57]
	v_pk_add_f32 v[28:29], v[28:29], v[62:63]
	v_pk_add_f32 v[32:33], v[32:33], v[60:61]
	v_pk_add_f32 v[26:27], v[26:27], v[66:67]
	v_pk_add_f32 v[30:31], v[30:31], v[64:65]
	s_branch .Lrt_done

; __device__ __forceinline__ void unpack8(u32x4 w, float* f) { f[0] = bflo(w.x); f[1] = bfhi(w.x); f[2] = bflo(w.y); f[3] = bfhi(w.y); f[4] = bflo(w.z); f[5] = bfhi(w.z); f[6] = bflo(w.w); f[7] = bfhi(w.w); }
; __device__ __forceinline__ const unsigned char* xrow(const XBuf& b, int row) { return (row < b.split ? b.p0 : b.p1) + (size_t)row * (b.f32 ? 8192 : 4096); }
; __device__ __forceinline__ void xload8(const XBuf& b, int row, int col, float* v) {
;     const unsigned char* r = xrow(b, row);
;     if (b.f32) { const f32x4 a0 = *(const f32x4*)(r + (size_t)col * 4), a1 = *(const f32x4*)(r + (size_t)col * 4 + 16);
; #pragma unroll
;         for (int j = 0; j < 4; ++j) { v[j] = a0[j]; v[4 + j] = a1[j]; } }
;     else unpack8(*(const u32x4*)(r + (size_t)col * 2), v);
; template <class Order>
; __device__ __forceinline__ void reduce_tail(const Order& S, const float* PART, const float* gate, const XBuf xin, const XBuf xout, int lane, int wave, int G, int bx) {
;     ...
;             const float* gp = gate + (size_t)batch_of(row) * NMOD + col; const f32x4 g0 = *(const f32x4*)gp, g1 = *(const f32x4*)(gp + 4);
;             float xv[8], o[8]; xload8(xin, row, col, xv);
.Lrt_done:
	v_add_u32_e32 v34, s24, v18
	v_add_u32_e32 v1, 0xffff8000, v34
	v_lshrrev_b32_e32 v1, 6, v1
	v_ashrrev_i32_e32 v0, 14, v34
	v_add_u32_e32 v1, 2, v1
	v_cmp_gt_i32_e32 vcc, s81, v34
	v_mov_b32_e32 v8, s48
	v_mov_b32_e32 v9, s46
	v_cndmask_b32_e32 v0, v1, v0, vcc
	v_mad_i64_i32 v[4:5], s[2:3], v0, s84, v[22:23]
	global_load_dwordx4 v[0:3], v[4:5], off offset:16
	s_nop 0
	global_load_dwordx4 v[4:7], v[4:5], off
	v_cmp_gt_i32_e32 vcc, s50, v34
	v_mov_b32_e32 v10, s47
	v_ashrrev_i32_e32 v35, 31, v34
	v_cndmask_b32_e32 v9, v8, v9, vcc
	v_mov_b32_e32 v8, s49
	v_cndmask_b32_e32 v8, v8, v10, vcc
	v_lshlrev_b64 v[10:11], s16, v[34:35]
	v_lshl_add_u64 v[36:37], v[8:9], 0, v[10:11]
	s_mov_b64 s[2:3], -1
	s_and_b64 vcc, exec, s[6:7]
	s_cbranch_vccz .LBB0_750
	v_lshl_add_u64 v[8:9], v[36:37], 0, v[24:25]
	global_load_dwordx4 v[12:15], v[8:9], off
	s_mov_b64 s[2:3], 0
	s_waitcnt vmcnt(0)
	v_lshlrev_b32_e32 v8, 16, v12
	v_and_b32_e32 v9, 0xffff0000, v12
	v_lshlrev_b32_e32 v10, 16, v13
	v_and_b32_e32 v11, 0xffff0000, v13
	v_lshlrev_b32_e32 v12, 16, v14
	v_and_b32_e32 v13, 0xffff0000, v14
	v_lshlrev_b32_e32 v14, 16, v15
	v_and_b32_e32 v15, 0xffff0000, v15
